# GEMM K-loop 2 (residual GEMMs): loop-control and next-iteration pointer selects hoisted into the last MFMA block
# baseline (speedup 1.0000x reference)
; #define PG8_STAGE(bufoff, gbase, voff) do { _Pragma("unroll") for (int _i = 0; _i < 2; ++_i) \
;         __builtin_amdgcn_global_load_lds((const unsigned*)((const char*)(gbase) + (voff)[_i]), (PG8_LAS unsigned*)(lds + (bufoff) + ldsw + _i * 8192), 16, 0, 0); } while (0)
; #define PG8_LDA(dst, b, h) do { _Pragma("unroll") for (int m = 0; m < 4; ++m) _Pragma("unroll") for (int k = 0; k < 2; ++k) dst[m][k] = *(const PG8_LAS bf16x8*)(lds + PG8_SA(b, h) + aoff + m * 2048 + k * 1024); } while (0)
; #define PG8_LDB(dst, b, h) do { _Pragma("unroll") for (int n = 0; n < 2; ++n) _Pragma("unroll") for (int k = 0; k < 2; ++k) dst[n][k] = *(const PG8_LAS bf16x8*)(lds + PG8_SB(b, h) + boff + n * 2048 + k * 1024); } while (0)
; #define PG8_WAIT_V(n) asm volatile("s_waitcnt vmcnt(" #n ")" ::: "memory")
; #define PG8_WAIT_L(n) asm volatile("s_waitcnt lgkmcnt(" #n ")" ::: "memory")
; #define PG8_BAR __builtin_amdgcn_s_barrier()
; template <class Epi, class Sched, bool ALIGN_EPI = false, bool SP2 = false>
; __device__ __forceinline__ void gemm_phase(PG8_LAS unsigned char* lds, const Gemm g, const Sched& S, const Epi& E) {
;     ...
;     for (;;) {
;         const bool has_next = S.next(ui + 1, nxt);
;         const char* nA = has_next ? (const char*)g.A + (size_t)nxt.pm * tstep : cA; const char* nB = has_next ? (const char*)g.Bt + (size_t)nxt.pn * tstep : cB;
;         for (int t = 0; t < nt; t += 2) {
;             const bool last = (t == nt - 2);
;             const char* a1 = cA + (size_t)(t + 1) * kstep;
;             const char* a2 = last ? nA : cA + (size_t)(t + 2) * kstep; const char* b2 = last ? nB : cB + (size_t)(t + 2) * kstep;
;             const char* a3 = a2 + kstep; const char* b3 = b2 + kstep;
;             if (last && has_next) S.a_ready(nxt);
;             if constexpr (SP2) {
;             PG8_LDB(B0, 0, 0); PG8_LDB(B1, 0, 1); PG8_SCHED; PG8_LDA(At, 0, 0); PG8_STAGE(PG8_SA(1, 1), a1 + hstep, voffA);
;             PG8_WAIT_V(8); PG8_WAIT_L(0); PG8_BAR; PG8_MMA(0, 0, At, B0); PG8_MMA(0, 1, At, B1); PG8_BAR; PG8_SCHED;
;     ...
; #pragma unroll
;         for (int a = 0; a < 2; ++a)
; #pragma unroll
;             for (int b = 0; b < 2; ++b)
; #pragma unroll
;                 for (int m = 0; m < 4; ++m)
; #pragma unroll
;                     for (int n = 0; n < 2; ++n) acc[a][b][m][n] = (f32x4){0.f, 0.f, 0.f, 0.f};
;         cur = nxt; cA = nA; cB = nB; ++ui;
.LBB0_202:
	s_add_u32 s24, s24, 0x80
	s_addc_u32 s25, s25, 0
	s_add_u32 s23, s28, 0x100
	v_mov_b32_e32 v8, 0
	s_addc_u32 s35, s29, 0
	s_mov_b32 s28, 0
	s_waitcnt lgkmcnt(0)
	v_mov_b32_e32 v9, v8
	v_mov_b32_e32 v10, v8
	v_mov_b32_e32 v11, v8
	v_mov_b32_e32 v12, v8
	v_mov_b32_e32 v13, v8
	v_mov_b32_e32 v14, v8
	v_mov_b32_e32 v15, v8
	v_mov_b32_e32 v24, v8
	v_mov_b32_e32 v25, v8
	v_mov_b32_e32 v26, v8
	v_mov_b32_e32 v27, v8
	v_mov_b32_e32 v28, v8
	v_mov_b32_e32 v29, v8
	v_mov_b32_e32 v30, v8
	v_mov_b32_e32 v31, v8
	v_mov_b32_e32 v40, v8
	v_mov_b32_e32 v41, v8
	v_mov_b32_e32 v42, v8
	v_mov_b32_e32 v43, v8
	v_mov_b32_e32 v44, v8
	v_mov_b32_e32 v45, v8
	v_mov_b32_e32 v46, v8
	v_mov_b32_e32 v47, v8
	v_mov_b32_e32 v56, v8
	v_mov_b32_e32 v57, v8
	v_mov_b32_e32 v58, v8
	v_mov_b32_e32 v59, v8
	v_mov_b32_e32 v60, v8
	v_mov_b32_e32 v61, v8
	v_mov_b32_e32 v62, v8
	v_mov_b32_e32 v63, v8
	v_mov_b32_e32 v16, v8
	v_mov_b32_e32 v17, v8
	v_mov_b32_e32 v18, v8
	v_mov_b32_e32 v19, v8
	v_mov_b32_e32 v20, v8
	v_mov_b32_e32 v21, v8
	v_mov_b32_e32 v22, v8
	v_mov_b32_e32 v23, v8
	v_mov_b32_e32 v32, v8
	v_mov_b32_e32 v33, v8
	v_mov_b32_e32 v34, v8
	v_mov_b32_e32 v35, v8
	v_mov_b32_e32 v36, v8
	v_mov_b32_e32 v37, v8
	v_mov_b32_e32 v38, v8
	v_mov_b32_e32 v39, v8
	v_mov_b32_e32 v48, v8
	v_mov_b32_e32 v49, v8
	v_mov_b32_e32 v50, v8
	v_mov_b32_e32 v51, v8
	v_mov_b32_e32 v52, v8
	v_mov_b32_e32 v53, v8
	v_mov_b32_e32 v54, v8
	v_mov_b32_e32 v55, v8
	v_mov_b32_e32 v64, v8
	v_mov_b32_e32 v65, v8
	v_mov_b32_e32 v66, v8
	v_mov_b32_e32 v67, v8
	v_mov_b32_e32 v68, v8
	v_mov_b32_e32 v69, v8
	v_mov_b32_e32 v70, v8
	v_mov_b32_e32 v71, v8
	v_mov_b32_e32 v72, v8
	v_mov_b32_e32 v73, v8
	v_mov_b32_e32 v74, v8
	v_mov_b32_e32 v75, v8
	v_mov_b32_e32 v76, v8
	v_mov_b32_e32 v77, v8
	v_mov_b32_e32 v78, v8
	v_mov_b32_e32 v79, v8
	v_mov_b32_e32 v88, v8
	v_mov_b32_e32 v89, v8
	v_mov_b32_e32 v90, v8
	v_mov_b32_e32 v91, v8
	v_mov_b32_e32 v92, v8
	v_mov_b32_e32 v93, v8
	v_mov_b32_e32 v94, v8
	v_mov_b32_e32 v95, v8
	v_mov_b32_e32 v104, v8
	v_mov_b32_e32 v105, v8
	v_mov_b32_e32 v106, v8
	v_mov_b32_e32 v107, v8
	v_mov_b32_e32 v108, v8
	v_mov_b32_e32 v109, v8
	v_mov_b32_e32 v110, v8
	v_mov_b32_e32 v111, v8
	v_mov_b32_e32 v120, v8
	v_mov_b32_e32 v121, v8
	v_mov_b32_e32 v122, v8
	v_mov_b32_e32 v123, v8
	v_mov_b32_e32 v124, v8
	v_mov_b32_e32 v125, v8
	v_mov_b32_e32 v126, v8
	v_mov_b32_e32 v127, v8
	v_mov_b32_e32 v80, v8
	v_mov_b32_e32 v81, v8
	v_mov_b32_e32 v82, v8
	v_mov_b32_e32 v83, v8
	v_mov_b32_e32 v84, v8
	v_mov_b32_e32 v85, v8
	v_mov_b32_e32 v86, v8
	v_mov_b32_e32 v87, v8
	v_mov_b32_e32 v96, v8
	v_mov_b32_e32 v97, v8
	v_mov_b32_e32 v98, v8
	v_mov_b32_e32 v99, v8
	v_mov_b32_e32 v100, v8
	v_mov_b32_e32 v101, v8
	v_mov_b32_e32 v102, v8
	v_mov_b32_e32 v103, v8
	v_mov_b32_e32 v112, v8
	v_mov_b32_e32 v113, v8
	v_mov_b32_e32 v114, v8
	v_mov_b32_e32 v115, v8
	v_mov_b32_e32 v116, v8
	v_mov_b32_e32 v117, v8
	v_mov_b32_e32 v118, v8
	v_mov_b32_e32 v119, v8
	v_mov_b32_e32 v128, v8
	v_mov_b32_e32 v129, v8
	v_mov_b32_e32 v130, v8
	v_mov_b32_e32 v131, v8
	v_mov_b32_e32 v132, v8
	v_mov_b32_e32 v133, v8
	v_mov_b32_e32 v134, v8
	v_mov_b32_e32 v135, v8
	s_add_i32 s36, s28, 2
	s_add_u32 s16, s24, 0x80
	s_addc_u32 s17, s25, 0
	s_cmp_eq_u32 s60, s28
	s_cselect_b32 s29, s3, s17
	s_cselect_b32 s28, s2, s16
	s_cselect_b32 s17, s9, s35
	s_cselect_b32 s16, s8, s23
.LBB0_203:
	s_add_i32 s18, 0, 0x10000
	v_add_u32_e32 v137, s18, v200
	s_add_i32 s19, 0, 0x14000
	ds_read_b128 v[144:147], v137
	ds_read_b128 v[148:151], v137 offset:1024
	ds_read_b128 v[152:155], v137 offset:2048
	ds_read_b128 v[156:159], v137 offset:3072
	v_add_u32_e32 v137, s19, v200
	ds_read_b128 v[160:163], v137
	ds_read_b128 v[178:181], v137 offset:1024
	ds_read_b128 v[182:185], v137 offset:2048
	ds_read_b128 v[186:189], v137 offset:3072
	v_lshl_add_u64 v[198:199], s[24:25], 0, v[140:141]
	s_add_i32 m0, s52, 0xc000
	ds_read_b128 v[190:193], v210
	ds_read_b128 v[194:197], v210 offset:1024
	ds_read_b128 v[212:215], v210 offset:2048
	ds_read_b128 v[216:219], v210 offset:3072
	ds_read_b128 v[220:223], v210 offset:4096
	ds_read_b128 v[224:227], v210 offset:5120
	ds_read_b128 v[228:231], v210 offset:6144
	ds_read_b128 v[232:235], v210 offset:7168
	global_load_lds_dwordx4 v[198:199], off
	v_lshl_add_u64 v[198:199], s[24:25], 0, v[142:143]
	s_add_i32 m0, s52, 0xe000
	s_nop 0
	global_load_lds_dwordx4 v[198:199], off
	s_waitcnt vmcnt(8)
	s_waitcnt lgkmcnt(0)
	s_barrier
	s_waitcnt lgkmcnt(0)
	v_mfma_f32_16x16x32_bf16 v[132:135], v[144:147], v[190:193], v[132:135]
	v_mfma_f32_16x16x32_bf16 v[128:131], v[152:155], v[190:193], v[128:131]
	v_mfma_f32_16x16x32_bf16 v[116:119], v[144:147], v[212:215], v[116:119]
	v_mfma_f32_16x16x32_bf16 v[112:115], v[152:155], v[212:215], v[112:115]
	s_setprio 1
	v_mfma_f32_16x16x32_bf16 v[100:103], v[144:147], v[220:223], v[100:103]
	v_mfma_f32_16x16x32_bf16 v[96:99], v[152:155], v[220:223], v[96:99]
	v_mfma_f32_16x16x32_bf16 v[84:87], v[144:147], v[228:231], v[84:87]
	v_mfma_f32_16x16x32_bf16 v[80:83], v[152:155], v[228:231], v[80:83]
	v_mfma_f32_16x16x32_bf16 v[132:135], v[148:151], v[194:197], v[132:135]
	v_mfma_f32_16x16x32_bf16 v[128:131], v[156:159], v[194:197], v[128:131]
	v_mfma_f32_16x16x32_bf16 v[116:119], v[148:151], v[216:219], v[116:119]
	v_mfma_f32_16x16x32_bf16 v[112:115], v[156:159], v[216:219], v[112:115]
	v_mfma_f32_16x16x32_bf16 v[100:103], v[148:151], v[224:227], v[100:103]
	v_mfma_f32_16x16x32_bf16 v[96:99], v[156:159], v[224:227], v[96:99]
	v_mfma_f32_16x16x32_bf16 v[84:87], v[148:151], v[232:235], v[84:87]
	v_mfma_f32_16x16x32_bf16 v[80:83], v[156:159], v[232:235], v[80:83]
	s_setprio 0
	s_setprio 1
	v_mfma_f32_16x16x32_bf16 v[124:127], v[160:163], v[190:193], v[124:127]
	v_mfma_f32_16x16x32_bf16 v[120:123], v[182:185], v[190:193], v[120:123]
	v_mfma_f32_16x16x32_bf16 v[108:111], v[160:163], v[212:215], v[108:111]
	v_mfma_f32_16x16x32_bf16 v[104:107], v[182:185], v[212:215], v[104:107]
	v_mfma_f32_16x16x32_bf16 v[92:95], v[160:163], v[220:223], v[92:95]
	v_mfma_f32_16x16x32_bf16 v[88:91], v[182:185], v[220:223], v[88:91]
	v_mfma_f32_16x16x32_bf16 v[76:79], v[160:163], v[228:231], v[76:79]
	v_mfma_f32_16x16x32_bf16 v[72:75], v[182:185], v[228:231], v[72:75]
	v_mfma_f32_16x16x32_bf16 v[124:127], v[178:181], v[194:197], v[124:127]
	v_mfma_f32_16x16x32_bf16 v[120:123], v[186:189], v[194:197], v[120:123]
	v_mfma_f32_16x16x32_bf16 v[108:111], v[178:181], v[216:219], v[108:111]
	v_mfma_f32_16x16x32_bf16 v[104:107], v[186:189], v[216:219], v[104:107]
	s_barrier
; #define PG8_STAGE(bufoff, gbase, voff) do { _Pragma("unroll") for (int _i = 0; _i < 2; ++_i) \
;         __builtin_amdgcn_global_load_lds((const unsigned*)((const char*)(gbase) + (voff)[_i]), (PG8_LAS unsigned*)(lds + (bufoff) + ldsw + _i * 8192), 16, 0, 0); } while (0)
; #define PG8_LDA(dst, b, h) do { _Pragma("unroll") for (int m = 0; m < 4; ++m) _Pragma("unroll") for (int k = 0; k < 2; ++k) dst[m][k] = *(const PG8_LAS bf16x8*)(lds + PG8_SA(b, h) + aoff + m * 2048 + k * 1024); } while (0)
; #define PG8_LDB(dst, b, h) do { _Pragma("unroll") for (int n = 0; n < 2; ++n) _Pragma("unroll") for (int k = 0; k < 2; ++k) dst[n][k] = *(const PG8_LAS bf16x8*)(lds + PG8_SB(b, h) + boff + n * 2048 + k * 1024); } while (0)
; #define PG8_MMA(ai, bj, At, Bt) do { __builtin_amdgcn_s_setprio(1); _Pragma("unroll") for (int m = 0; m < 4; ++m) _Pragma("unroll") for (int n = 0; n < 2; ++n) _Pragma("unroll") for (int k = 0; k < 2; ++k) \
;         acc[ai][bj][m][n] = __builtin_amdgcn_mfma_f32_16x16x32_bf16(Bt[n][k], At[m][k], acc[ai][bj][m][n], 0, 0, 0); __builtin_amdgcn_s_setprio(0); } while (0)
; #define PG8_WAIT_V(n) asm volatile("s_waitcnt vmcnt(" #n ")" ::: "memory")
; #define PG8_WAIT_L(n) asm volatile("s_waitcnt lgkmcnt(" #n ")" ::: "memory")
; #define PG8_BAR __builtin_amdgcn_s_barrier()
; #define PG8_SCHED __builtin_amdgcn_sched_barrier(0)
; template <class Epi, class Sched, bool ALIGN_EPI = false, bool SP2 = false>
; __device__ __forceinline__ void gemm_phase(PG8_LAS unsigned char* lds, const Gemm g, const Sched& S, const Epi& E) {
;     ...
;             PG8_WAIT_V(8); PG8_WAIT_L(0); PG8_BAR; PG8_MMA(0, 0, At, B0); PG8_MMA(0, 1, At, B1); PG8_BAR; PG8_SCHED;
;             PG8_LDA(At, 0, 1); PG8_STAGE(PG8_SB(0, 0), b2, voffB); PG8_STAGE(PG8_SB(0, 1), b2 + hstep, voffB); PG8_STAGE(PG8_SA(0, 0), a2, voffA);
;             PG8_WAIT_V(8); PG8_WAIT_L(0); PG8_BAR; PG8_MMA(1, 0, At, B0); PG8_MMA(1, 1, At, B1); PG8_BAR; PG8_SCHED;
;             PG8_LDB(B0, 1, 0); PG8_LDB(B1, 1, 1); PG8_SCHED; PG8_LDA(At, 1, 0); PG8_STAGE(PG8_SA(0, 1), a2 + hstep, voffA);
	v_mfma_f32_16x16x32_bf16 v[92:95], v[178:181], v[224:227], v[92:95]
	v_mfma_f32_16x16x32_bf16 v[88:91], v[186:189], v[224:227], v[88:91]
	v_mfma_f32_16x16x32_bf16 v[76:79], v[178:181], v[232:235], v[76:79]
	v_mfma_f32_16x16x32_bf16 v[72:75], v[186:189], v[232:235], v[72:75]
	s_setprio 0
	s_add_i32 s18, s18, s41
	v_lshl_add_u64 v[198:199], s[16:17], 0, v[0:1]
	s_mov_b32 m0, s18
	ds_read_b128 v[190:193], v210 offset:16384
	ds_read_b128 v[194:197], v210 offset:17408
	ds_read_b128 v[212:215], v210 offset:18432
	ds_read_b128 v[216:219], v210 offset:19456
	ds_read_b128 v[220:223], v210 offset:20480
	ds_read_b128 v[224:227], v210 offset:21504
	ds_read_b128 v[228:231], v210 offset:22528
	ds_read_b128 v[232:235], v210 offset:23552
	global_load_lds_dwordx4 v[198:199], off
	s_add_i32 m0, s18, 0x2000
	v_lshl_add_u64 v[236:237], s[16:17], 0, v[2:3]
	s_add_u32 s16, s16, s12
	s_addc_u32 s17, s17, 0
	s_add_i32 s18, s19, s41
	global_load_lds_dwordx4 v[236:237], off
	v_lshl_add_u64 v[238:239], s[16:17], 0, v[0:1]
	s_mov_b32 m0, s18
	v_lshl_add_u64 v[240:241], s[16:17], 0, v[2:3]
	global_load_lds_dwordx4 v[238:239], off
	s_add_i32 m0, s18, 0x2000
	v_lshl_add_u64 v[242:243], s[28:29], 0, v[0:1]
	global_load_lds_dwordx4 v[240:241], off
	v_lshl_add_u64 v[244:245], s[28:29], 0, v[2:3]
	s_waitcnt vmcnt(6)
	s_waitcnt lgkmcnt(0)
	s_barrier
	s_waitcnt lgkmcnt(0)
	v_mfma_f32_16x16x32_bf16 v[68:71], v[144:147], v[190:193], v[68:71]
	v_mfma_f32_16x16x32_bf16 v[64:67], v[152:155], v[190:193], v[64:67]
	v_mfma_f32_16x16x32_bf16 v[52:55], v[144:147], v[212:215], v[52:55]
	s_mov_b32 m0, s52
	v_mfma_f32_16x16x32_bf16 v[48:51], v[152:155], v[212:215], v[48:51]
	s_setprio 1
	global_load_lds_dwordx4 v[242:243], off
	v_mfma_f32_16x16x32_bf16 v[36:39], v[144:147], v[220:223], v[36:39]
	v_mfma_f32_16x16x32_bf16 v[32:35], v[152:155], v[220:223], v[32:35]
	v_mfma_f32_16x16x32_bf16 v[20:23], v[144:147], v[228:231], v[20:23]
	v_mfma_f32_16x16x32_bf16 v[16:19], v[152:155], v[228:231], v[16:19]
	v_mfma_f32_16x16x32_bf16 v[68:71], v[148:151], v[194:197], v[68:71]
	v_mfma_f32_16x16x32_bf16 v[64:67], v[156:159], v[194:197], v[64:67]
	v_mfma_f32_16x16x32_bf16 v[52:55], v[148:151], v[216:219], v[52:55]
	s_mov_b32 m0, s53
	v_mfma_f32_16x16x32_bf16 v[48:51], v[156:159], v[216:219], v[48:51]
	global_load_lds_dwordx4 v[244:245], off
	v_mfma_f32_16x16x32_bf16 v[36:39], v[148:151], v[224:227], v[36:39]
	v_mfma_f32_16x16x32_bf16 v[32:35], v[156:159], v[224:227], v[32:35]
	v_mfma_f32_16x16x32_bf16 v[20:23], v[148:151], v[232:235], v[20:23]
	v_mfma_f32_16x16x32_bf16 v[16:19], v[156:159], v[232:235], v[16:19]
	s_setprio 0
	s_setprio 1
	v_mfma_f32_16x16x32_bf16 v[60:63], v[160:163], v[190:193], v[60:63]
	v_mfma_f32_16x16x32_bf16 v[56:59], v[182:185], v[190:193], v[56:59]
	v_mfma_f32_16x16x32_bf16 v[44:47], v[160:163], v[212:215], v[44:47]
	v_mfma_f32_16x16x32_bf16 v[40:43], v[182:185], v[212:215], v[40:43]
	v_mfma_f32_16x16x32_bf16 v[28:31], v[160:163], v[220:223], v[28:31]
	v_mfma_f32_16x16x32_bf16 v[24:27], v[182:185], v[220:223], v[24:27]
	v_mfma_f32_16x16x32_bf16 v[12:15], v[160:163], v[228:231], v[12:15]
	v_mfma_f32_16x16x32_bf16 v[8:11], v[182:185], v[228:231], v[8:11]
	v_mfma_f32_16x16x32_bf16 v[60:63], v[178:181], v[194:197], v[60:63]
	v_mfma_f32_16x16x32_bf16 v[56:59], v[186:189], v[194:197], v[56:59]
	v_mfma_f32_16x16x32_bf16 v[44:47], v[178:181], v[216:219], v[44:47]
	v_mfma_f32_16x16x32_bf16 v[40:43], v[186:189], v[216:219], v[40:43]
	s_barrier
	v_mfma_f32_16x16x32_bf16 v[28:31], v[178:181], v[224:227], v[28:31]
	v_mfma_f32_16x16x32_bf16 v[24:27], v[186:189], v[224:227], v[24:27]
	v_mfma_f32_16x16x32_bf16 v[12:15], v[178:181], v[232:235], v[12:15]
	v_mfma_f32_16x16x32_bf16 v[8:11], v[186:189], v[232:235], v[8:11]
	s_setprio 0
	s_add_i32 s18, 0, 0x18000
	v_add_u32_e32 v137, s18, v200
	ds_read_b128 v[144:147], v137
	ds_read_b128 v[148:151], v137 offset:1024
	ds_read_b128 v[152:155], v137 offset:2048
	ds_read_b128 v[156:159], v137 offset:3072
	v_add_u32_e32 v137, s33, v200
	ds_read_b128 v[160:163], v137
	ds_read_b128 v[178:181], v137 offset:1024
	ds_read_b128 v[182:185], v137 offset:2048
	ds_read_b128 v[186:189], v137 offset:3072
	s_add_u32 s16, s28, s12
	s_addc_u32 s17, s29, 0
	s_mov_b32 m0, s54
	v_lshl_add_u64 v[246:247], s[16:17], 0, v[0:1]
	ds_read_b128 v[190:193], v210 offset:32768
	ds_read_b128 v[194:197], v210 offset:33792
	ds_read_b128 v[212:215], v210 offset:34816
	ds_read_b128 v[216:219], v210 offset:35840
	ds_read_b128 v[220:223], v210 offset:36864
	ds_read_b128 v[224:227], v210 offset:37888
	ds_read_b128 v[228:231], v210 offset:38912
	ds_read_b128 v[232:235], v210 offset:39936
	global_load_lds_dwordx4 v[246:247], off
	v_lshl_add_u64 v[246:247], s[16:17], 0, v[2:3]
	s_mov_b32 m0, s55
	s_nop 0
	global_load_lds_dwordx4 v[246:247], off
	s_waitcnt vmcnt(8)
	s_waitcnt lgkmcnt(0)
	s_barrier
; #define PG8_STAGE(bufoff, gbase, voff) do { _Pragma("unroll") for (int _i = 0; _i < 2; ++_i) \
;         __builtin_amdgcn_global_load_lds((const unsigned*)((const char*)(gbase) + (voff)[_i]), (PG8_LAS unsigned*)(lds + (bufoff) + ldsw + _i * 8192), 16, 0, 0); } while (0)
; #define PG8_LDA(dst, b, h) do { _Pragma("unroll") for (int m = 0; m < 4; ++m) _Pragma("unroll") for (int k = 0; k < 2; ++k) dst[m][k] = *(const PG8_LAS bf16x8*)(lds + PG8_SA(b, h) + aoff + m * 2048 + k * 1024); } while (0)
; #define PG8_MMA(ai, bj, At, Bt) do { __builtin_amdgcn_s_setprio(1); _Pragma("unroll") for (int m = 0; m < 4; ++m) _Pragma("unroll") for (int n = 0; n < 2; ++n) _Pragma("unroll") for (int k = 0; k < 2; ++k) \
;         acc[ai][bj][m][n] = __builtin_amdgcn_mfma_f32_16x16x32_bf16(Bt[n][k], At[m][k], acc[ai][bj][m][n], 0, 0, 0); __builtin_amdgcn_s_setprio(0); } while (0)
; #define PG8_WAIT_V(n) asm volatile("s_waitcnt vmcnt(" #n ")" ::: "memory")
; #define PG8_WAIT_L(n) asm volatile("s_waitcnt lgkmcnt(" #n ")" ::: "memory")
; #define PG8_BAR __builtin_amdgcn_s_barrier()
; #define PG8_SCHED __builtin_amdgcn_sched_barrier(0)
; template <class Epi, class Sched, bool ALIGN_EPI = false, bool SP2 = false>
; __device__ __forceinline__ void gemm_phase(PG8_LAS unsigned char* lds, const Gemm g, const Sched& S, const Epi& E) {
;     ...
;         for (int t = 0; t < nt; t += 2) {
;             const bool last = (t == nt - 2);
;             const char* a1 = cA + (size_t)(t + 1) * kstep;
;             const char* a2 = last ? nA : cA + (size_t)(t + 2) * kstep; const char* b2 = last ? nB : cB + (size_t)(t + 2) * kstep;
;             const char* a3 = a2 + kstep; const char* b3 = b2 + kstep;
;     ...
;             PG8_WAIT_V(8); PG8_WAIT_L(0); PG8_BAR; PG8_MMA(0, 0, At, B0); PG8_MMA(0, 1, At, B1); PG8_BAR; PG8_SCHED;
;             PG8_LDA(At, 1, 1); PG8_STAGE(PG8_SB(1, 0), b3, voffB); PG8_STAGE(PG8_SB(1, 1), b3 + hstep, voffB); PG8_STAGE(PG8_SA(1, 0), a3, voffA);
;             PG8_WAIT_V(8); PG8_WAIT_L(0); PG8_BAR; PG8_MMA(1, 0, At, B0); PG8_MMA(1, 1, At, B1); PG8_BAR; PG8_SCHED;
	s_waitcnt lgkmcnt(0)
	v_mfma_f32_16x16x32_bf16 v[132:135], v[144:147], v[190:193], v[132:135]
	v_mfma_f32_16x16x32_bf16 v[128:131], v[152:155], v[190:193], v[128:131]
	v_mfma_f32_16x16x32_bf16 v[116:119], v[144:147], v[212:215], v[116:119]
	v_mfma_f32_16x16x32_bf16 v[112:115], v[152:155], v[212:215], v[112:115]
	s_setprio 1
	v_mfma_f32_16x16x32_bf16 v[100:103], v[144:147], v[220:223], v[100:103]
	v_mfma_f32_16x16x32_bf16 v[96:99], v[152:155], v[220:223], v[96:99]
	v_mfma_f32_16x16x32_bf16 v[84:87], v[144:147], v[228:231], v[84:87]
	v_mfma_f32_16x16x32_bf16 v[80:83], v[152:155], v[228:231], v[80:83]
	v_mfma_f32_16x16x32_bf16 v[132:135], v[148:151], v[194:197], v[132:135]
	v_mfma_f32_16x16x32_bf16 v[128:131], v[156:159], v[194:197], v[128:131]
	v_mfma_f32_16x16x32_bf16 v[116:119], v[148:151], v[216:219], v[116:119]
	v_mfma_f32_16x16x32_bf16 v[112:115], v[156:159], v[216:219], v[112:115]
	v_mfma_f32_16x16x32_bf16 v[100:103], v[148:151], v[224:227], v[100:103]
	v_mfma_f32_16x16x32_bf16 v[96:99], v[156:159], v[224:227], v[96:99]
	v_mfma_f32_16x16x32_bf16 v[84:87], v[148:151], v[232:235], v[84:87]
	v_mfma_f32_16x16x32_bf16 v[80:83], v[156:159], v[232:235], v[80:83]
	s_setprio 0
	s_setprio 1
	v_mfma_f32_16x16x32_bf16 v[124:127], v[160:163], v[190:193], v[124:127]
	v_mfma_f32_16x16x32_bf16 v[120:123], v[182:185], v[190:193], v[120:123]
	v_mfma_f32_16x16x32_bf16 v[108:111], v[160:163], v[212:215], v[108:111]
	v_mfma_f32_16x16x32_bf16 v[104:107], v[182:185], v[212:215], v[104:107]
	v_mfma_f32_16x16x32_bf16 v[92:95], v[160:163], v[220:223], v[92:95]
	v_mfma_f32_16x16x32_bf16 v[88:91], v[182:185], v[220:223], v[88:91]
	v_mfma_f32_16x16x32_bf16 v[76:79], v[160:163], v[228:231], v[76:79]
	v_mfma_f32_16x16x32_bf16 v[72:75], v[182:185], v[228:231], v[72:75]
	v_mfma_f32_16x16x32_bf16 v[124:127], v[178:181], v[194:197], v[124:127]
	v_mfma_f32_16x16x32_bf16 v[120:123], v[186:189], v[194:197], v[120:123]
	v_mfma_f32_16x16x32_bf16 v[108:111], v[178:181], v[216:219], v[108:111]
	v_mfma_f32_16x16x32_bf16 v[104:107], v[186:189], v[216:219], v[104:107]
	s_barrier
	v_mfma_f32_16x16x32_bf16 v[92:95], v[178:181], v[224:227], v[92:95]
	v_mfma_f32_16x16x32_bf16 v[88:91], v[186:189], v[224:227], v[88:91]
	v_mfma_f32_16x16x32_bf16 v[76:79], v[178:181], v[232:235], v[76:79]
	v_mfma_f32_16x16x32_bf16 v[72:75], v[186:189], v[232:235], v[72:75]
	s_setprio 0
	s_add_i32 s16, s18, s41
	v_lshl_add_u64 v[198:199], v[198:199], 0, s[20:21]
	s_mov_b32 m0, s16
	ds_read_b128 v[190:193], v210 offset:49152
	ds_read_b128 v[194:197], v210 offset:50176
	ds_read_b128 v[212:215], v210 offset:51200
	ds_read_b128 v[216:219], v210 offset:52224
	ds_read_b128 v[220:223], v210 offset:53248
	ds_read_b128 v[224:227], v210 offset:54272
	ds_read_b128 v[228:231], v210 offset:55296
	ds_read_b128 v[232:235], v210 offset:56320
	global_load_lds_dwordx4 v[198:199], off
	v_lshl_add_u64 v[198:199], v[236:237], 0, s[20:21]
	s_add_i32 m0, s16, 0x2000
	s_add_i32 s16, s33, s41
	global_load_lds_dwordx4 v[198:199], off
	v_lshl_add_u64 v[198:199], v[238:239], 0, s[20:21]
	s_mov_b32 m0, s16
	s_nop 0
	global_load_lds_dwordx4 v[198:199], off
	v_lshl_add_u64 v[198:199], v[240:241], 0, s[20:21]
	s_add_i32 m0, s16, 0x2000
	s_nop 0
	global_load_lds_dwordx4 v[198:199], off
	v_lshl_add_u64 v[198:199], v[242:243], 0, s[20:21]
	v_lshl_add_u64 v[244:245], v[244:245], 0, s[20:21]
	s_waitcnt vmcnt(6)
	s_waitcnt lgkmcnt(0)
	s_barrier
	s_waitcnt lgkmcnt(0)
	v_mfma_f32_16x16x32_bf16 v[68:71], v[144:147], v[190:193], v[68:71]
	v_mfma_f32_16x16x32_bf16 v[64:67], v[152:155], v[190:193], v[64:67]
	v_mfma_f32_16x16x32_bf16 v[52:55], v[144:147], v[212:215], v[52:55]
	s_mov_b32 m0, s56
	v_mfma_f32_16x16x32_bf16 v[48:51], v[152:155], v[212:215], v[48:51]
	s_setprio 1
	global_load_lds_dwordx4 v[198:199], off
	v_mfma_f32_16x16x32_bf16 v[36:39], v[144:147], v[220:223], v[36:39]
	v_mfma_f32_16x16x32_bf16 v[32:35], v[152:155], v[220:223], v[32:35]
	v_mfma_f32_16x16x32_bf16 v[20:23], v[144:147], v[228:231], v[20:23]
	s_add_u32 s24, s24, 0x100
	s_addc_u32 s25, s25, 0
	v_mfma_f32_16x16x32_bf16 v[16:19], v[152:155], v[228:231], v[16:19]
	s_add_u32 s23, s23, 0x100
	s_addc_u32 s35, s35, 0
	v_mfma_f32_16x16x32_bf16 v[68:71], v[148:151], v[194:197], v[68:71]
	s_add_u32 s16, s24, 0x80
	s_addc_u32 s17, s25, 0
	v_mfma_f32_16x16x32_bf16 v[64:67], v[156:159], v[194:197], v[64:67]
	s_cmp_eq_u32 s60, s36
	s_cselect_b32 s29, s3, s17
	s_cselect_b32 s28, s2, s16
	v_mfma_f32_16x16x32_bf16 v[52:55], v[148:151], v[216:219], v[52:55]
	s_cselect_b32 s17, s9, s35
	s_cselect_b32 s16, s8, s23
	s_mov_b32 m0, s57
	v_mfma_f32_16x16x32_bf16 v[48:51], v[156:159], v[216:219], v[48:51]
	s_add_i32 s36, s36, 2
	global_load_lds_dwordx4 v[244:245], off
	v_mfma_f32_16x16x32_bf16 v[36:39], v[148:151], v[224:227], v[36:39]
	v_mfma_f32_16x16x32_bf16 v[32:35], v[156:159], v[224:227], v[32:35]
	v_mfma_f32_16x16x32_bf16 v[20:23], v[148:151], v[232:235], v[20:23]
	v_mfma_f32_16x16x32_bf16 v[16:19], v[156:159], v[232:235], v[16:19]
	s_setprio 0
	s_setprio 1
	v_mfma_f32_16x16x32_bf16 v[60:63], v[160:163], v[190:193], v[60:63]
	v_mfma_f32_16x16x32_bf16 v[56:59], v[182:185], v[190:193], v[56:59]
	v_mfma_f32_16x16x32_bf16 v[44:47], v[160:163], v[212:215], v[44:47]
	v_mfma_f32_16x16x32_bf16 v[40:43], v[182:185], v[212:215], v[40:43]
	v_mfma_f32_16x16x32_bf16 v[28:31], v[160:163], v[220:223], v[28:31]
	v_mfma_f32_16x16x32_bf16 v[24:27], v[182:185], v[220:223], v[24:27]
	v_mfma_f32_16x16x32_bf16 v[12:15], v[160:163], v[228:231], v[12:15]
	v_mfma_f32_16x16x32_bf16 v[8:11], v[182:185], v[228:231], v[8:11]
	v_mfma_f32_16x16x32_bf16 v[60:63], v[178:181], v[194:197], v[60:63]
	v_mfma_f32_16x16x32_bf16 v[56:59], v[186:189], v[194:197], v[56:59]
	v_mfma_f32_16x16x32_bf16 v[44:47], v[178:181], v[216:219], v[44:47]
	v_mfma_f32_16x16x32_bf16 v[40:43], v[186:189], v[216:219], v[40:43]
	s_barrier
	v_mfma_f32_16x16x32_bf16 v[28:31], v[178:181], v[224:227], v[28:31]
	v_mfma_f32_16x16x32_bf16 v[24:27], v[186:189], v[224:227], v[24:27]
	v_mfma_f32_16x16x32_bf16 v[12:15], v[178:181], v[232:235], v[12:15]
	v_mfma_f32_16x16x32_bf16 v[8:11], v[186:189], v[232:235], v[8:11]
	s_setprio 0
	s_add_i32 s18, s59, 2
	s_cmp_ge_u32 s36, s18
	s_cbranch_scc0 .LBB0_203
	s_and_b64 vcc, exec, s[46:47]
	s_cbranch_vccz .LBB0_206
	s_barrier
	s_setprio 1
